# RWKV scanner waves at s_setprio 2 instead of 3 (stager waves stay at 0)
# speedup vs baseline: 1.0044x; 1.0044x over previous
; template <int CPL>
; DI void scan_block2(CP p, int layer, int s, int d, int hd, int rowhalf, char* smem) {
;     ...
;     constexpr int LPRW = 64 / CPL;
;     constexpr int NV = CPL / 2;
;     const int cg = lane % LPRW;
;     const int row = (CPL == 8 ? rowhalf * 32 + wv * 8 : wv * 16) + lane / LPRW;
;     f2 S[NV];
; #pragma unroll
;     for (int i = 0; i < NV; ++i) S[i] = mk2(0.f, 0.f);
;     __builtin_amdgcn_s_setprio(3);
;     __syncthreads();
.LBB0_181:
	s_or_b64 exec, exec, s[2:3]
	v_ashrrev_i32_e32 v0, 6, v2
	s_and_b32 s16, s82, 1
	v_cmp_gt_i32_e32 vcc, 4, v0
	v_lshlrev_b32_e32 v52, 3, v0
	s_waitcnt lgkmcnt(0)
	s_barrier
	s_and_saveexec_b64 s[2:3], vcc
	s_xor_b64 s[2:3], exec, s[2:3]
	s_cbranch_execz .LBB0_187
	s_setprio 2
	v_and_b32_e32 v0, 63, v179
	v_lshrrev_b32_e32 v202, 6, v179
	v_and_b32_e32 v203, 7, v0
	v_lshrrev_b32_e32 v204, 3, v0
	v_lshl_add_u32 v204, v202, 3, v204
	s_lshl_b32 s8, s16, 5
	v_add_u32_e32 v204, s8, v204
	v_lshlrev_b32_e32 v202, 5, v203
	v_lshlrev_b32_e32 v204, 2, v204
	v_add_u32_e32 v205, 0x500, v204
	v_add_u32_e32 v204, 0x18800, v204
	v_lshlrev_b32_e32 v206, 2, v0
	v_add_u32_e32 v206, 0x24800, v206
	v_cmp_eq_u32_e32 vcc, 0, v203
	v_mov_b32_e32 v170, 0
	v_mov_b32_e32 v171, 0
	v_mov_b32_e32 v172, 0
	v_mov_b32_e32 v173, 0
	v_mov_b32_e32 v174, 0
	v_mov_b32_e32 v175, 0
	v_mov_b32_e32 v176, 0
	v_mov_b32_e32 v177, 0
	s_mov_b32 s10, 0
	s_barrier
